# t8 + in-proj next-tile coordinates via shifts (group size is always 8 for 64x70 tiles) instead of the generic divide chain
# speedup vs baseline: 1.0029x; 1.0029x over previous
;     __device__ bool next(int i, Unit& u) const {
;         const long L = (long)i * G + c; if (L >= nwg) return false;
;         int wgid = (int)L; { const int q = nwg / NXCD, r = nwg % NXCD, xcd = wgid % NXCD, off = wgid / NXCD; wgid = (xcd < r ? xcd * (q + 1) : r * (q + 1) + (xcd - r) * q) + off; }
;         const int nig = WGM * nN, gid = wgid / nig, fm = gid * WGM, gsz = (nM - fm) < WGM ? (nM - fm) : WGM;
;         u.pm = fm + ((wgid % nig) % gsz); u.pn = (wgid % nig) / gsz; return true;
;     }
.LBB0_344:
	s_add_i32 s62, s62, 1
	s_mul_i32 s11, s62, s58
	s_mul_hi_u32 s15, s62, s17
	s_add_i32 s15, s15, s11
	s_mul_i32 s11, s62, s17
	s_add_u32 s40, s11, s23
	s_addc_u32 s41, s15, s59
	v_cmp_gt_i64_e32 vcc, s[40:41], v[200:201]
	v_cmp_lt_i64_e64 s[36:37], s[40:41], v[198:199]
	s_cbranch_vccnz .LBB0_346
	s_and_b32 s10, s40, 7
	s_lshl_b32 s15, s10, 3
	s_bfe_u32 s11, s40, 0x30003
	s_add_i32 s30, s15, s11
	s_lshr_b32 s10, s40, 6
